# SwiGLU epilogue rewrite + mlstm_local full-line write-through state stores + write-through prologue stores
# baseline (speedup 1.0000x reference)
.LBB0_107:
	ds_read2_b32 v[132:133], v37 offset1:8
	ds_read2_b32 v[134:135], v37 offset0:33 offset1:41
	ds_read2_b32 v[136:137], v37 offset0:66 offset1:74
	ds_read2_b32 v[138:139], v37 offset0:99 offset1:107
	ds_read2_b32 v[140:141], v37 offset0:132 offset1:140
	ds_read2_b32 v[142:143], v37 offset0:165 offset1:173
	ds_read2_b32 v[144:145], v37 offset0:198 offset1:206
	ds_read2_b32 v[146:147], v37 offset0:231 offset1:239
	s_waitcnt lgkmcnt(7)
	v_mov_b32_e32 v128, v132
	s_waitcnt lgkmcnt(6)
	v_mov_b32_e32 v129, v134
	s_waitcnt lgkmcnt(5)
	v_mov_b32_e32 v130, v136
	s_waitcnt lgkmcnt(4)
	v_mov_b32_e32 v131, v138
	v_pk_mul_f32 v[128:129], v[114:115], v[128:129]
	v_pk_mul_f32 v[130:131], v[116:117], v[130:131]
	v_cvt_pk_bf16_f32 v128, v128, v129
	v_cvt_pk_bf16_f32 v129, v130, v131
	s_waitcnt lgkmcnt(3)
	v_mov_b32_e32 v130, v140
	s_waitcnt lgkmcnt(2)
	v_mov_b32_e32 v131, v142
	s_waitcnt lgkmcnt(1)
	v_mov_b32_e32 v148, v144
	s_waitcnt lgkmcnt(0)
	v_mov_b32_e32 v149, v146
	v_pk_mul_f32 v[130:131], v[118:119], v[130:131]
	v_pk_mul_f32 v[148:149], v[120:121], v[148:149]
	v_cvt_pk_bf16_f32 v130, v130, v131
	v_cvt_pk_bf16_f32 v131, v148, v149
	v_mad_i64_i32 v[148:149], s[0:1], s47, v102, 0
	v_lshl_add_u64 v[148:149], v[148:149], 1, s[4:5]
	v_lshl_add_u64 v[148:149], v[148:149], 0, v[38:39]
	v_mov_b32_e32 v134, v133
	v_mov_b32_e32 v138, v137
	global_store_dwordx4 v[148:149], v[128:131], off sc1
	v_mov_b32_e32 v142, v141
	v_mov_b32_e32 v146, v145
	v_pk_mul_f32 v[128:129], v[114:115], v[134:135]
	v_pk_mul_f32 v[130:131], v[116:117], v[138:139]
	v_cvt_pk_bf16_f32 v128, v128, v129
	v_cvt_pk_bf16_f32 v129, v130, v131
	v_pk_mul_f32 v[130:131], v[118:119], v[142:143]
	v_pk_mul_f32 v[132:133], v[120:121], v[146:147]
	v_cvt_pk_bf16_f32 v130, v130, v131
	v_cvt_pk_bf16_f32 v131, v132, v133
	v_mad_i64_i32 v[132:133], s[0:1], s47, v106, 0
	v_lshl_add_u64 v[132:133], v[132:133], 1, s[4:5]
	v_lshl_add_u64 v[132:133], v[132:133], 0, v[38:39]
	ds_read2_b32 v[134:135], v37 offset0:16 offset1:24
	ds_read2_b32 v[136:137], v37 offset0:49 offset1:57
	global_store_dwordx4 v[132:133], v[128:131], off sc1
	ds_read2_b32 v[132:133], v37 offset0:82 offset1:90
	ds_read2_b32 v[138:139], v37 offset0:115 offset1:123
	ds_read2_b32 v[140:141], v37 offset0:148 offset1:156
	ds_read2_b32 v[142:143], v37 offset0:181 offset1:189
	ds_read2_b32 v[144:145], v37 offset0:214 offset1:222
	ds_read2_b32 v[146:147], v37 offset0:247 offset1:255
	s_waitcnt lgkmcnt(7)
	v_mov_b32_e32 v128, v134
	s_waitcnt lgkmcnt(6)
	v_mov_b32_e32 v129, v136
	s_waitcnt lgkmcnt(5)
	v_mov_b32_e32 v130, v132
	s_waitcnt lgkmcnt(4)
	v_mov_b32_e32 v131, v138
	v_pk_mul_f32 v[128:129], v[114:115], v[128:129]
	v_pk_mul_f32 v[130:131], v[116:117], v[130:131]
	v_mov_b32_e32 v136, v135
	v_mov_b32_e32 v138, v133
	v_cvt_pk_bf16_f32 v128, v128, v129
	v_cvt_pk_bf16_f32 v129, v130, v131
	s_waitcnt lgkmcnt(3)
	v_mov_b32_e32 v130, v140
	s_waitcnt lgkmcnt(2)
	v_mov_b32_e32 v131, v142
	s_waitcnt lgkmcnt(1)
	v_mov_b32_e32 v148, v144
	s_waitcnt lgkmcnt(0)
	v_mov_b32_e32 v149, v146
	v_pk_mul_f32 v[114:115], v[114:115], v[136:137]
	v_pk_mul_f32 v[116:117], v[116:117], v[138:139]
	v_mov_b32_e32 v142, v141
	v_mov_b32_e32 v146, v145
	v_pk_mul_f32 v[130:131], v[118:119], v[130:131]
	v_pk_mul_f32 v[148:149], v[120:121], v[148:149]
	v_cvt_pk_bf16_f32 v114, v114, v115
	v_cvt_pk_bf16_f32 v115, v116, v117
	v_pk_mul_f32 v[116:117], v[118:119], v[142:143]
	v_pk_mul_f32 v[118:119], v[120:121], v[146:147]
	v_cvt_pk_bf16_f32 v130, v130, v131
	v_cvt_pk_bf16_f32 v131, v148, v149
	v_mad_i64_i32 v[148:149], s[0:1], s47, v108, 0
	v_cvt_pk_bf16_f32 v116, v116, v117
	v_cvt_pk_bf16_f32 v117, v118, v119
	v_mad_i64_i32 v[118:119], s[0:1], s47, v110, 0
	v_lshl_add_u64 v[148:149], v[148:149], 1, s[4:5]
	v_lshl_add_u64 v[118:119], v[118:119], 1, s[4:5]
	v_lshl_add_u64 v[148:149], v[148:149], 0, v[38:39]
	v_lshl_add_u64 v[118:119], v[118:119], 0, v[38:39]
	s_andn2_b64 vcc, exec, s[22:23]
	global_store_dwordx4 v[148:149], v[128:131], off sc1
	global_store_dwordx4 v[118:119], v[114:117], off sc1
	s_cbranch_vccnz .LBB0_65
	s_add_i32 s75, s75, s96
	s_cmpk_gt_i32 s75, 0x5a7f
	s_cselect_b64 s[22:23], -1, 0
	s_and_b64 vcc, exec, s[22:23]
	s_cbranch_vccnz .LBB0_152
	s_cmpk_gt_i32 s75, 0x5ff
	s_cselect_b64 s[36:37], -1, 0
	s_cmpk_lt_i32 s75, 0x600
	s_mov_b64 s[0:1], -1
	s_cbranch_scc1 .LBB0_111
	s_add_i32 s77, s75, 0xfffffa00
	s_mov_b64 s[0:1], 0

.LBB0_168:
	ds_read2_b32 v[124:125], v37 offset1:8
	ds_read2_b32 v[126:127], v37 offset0:33 offset1:41
	ds_read2_b32 v[128:129], v37 offset0:66 offset1:74
	ds_read2_b32 v[130:131], v37 offset0:99 offset1:107
	ds_read2_b32 v[132:133], v37 offset0:132 offset1:140
	ds_read2_b32 v[134:135], v37 offset0:165 offset1:173
	ds_read2_b32 v[136:137], v37 offset0:198 offset1:206
	ds_read2_b32 v[138:139], v37 offset0:231 offset1:239
	s_waitcnt lgkmcnt(7)
	v_mov_b32_e32 v120, v124
	s_waitcnt lgkmcnt(6)
	v_mov_b32_e32 v121, v126
	s_waitcnt lgkmcnt(5)
	v_mov_b32_e32 v122, v128
	s_waitcnt lgkmcnt(4)
	v_mov_b32_e32 v123, v130
	v_pk_mul_f32 v[120:121], v[114:115], v[120:121]
	v_pk_mul_f32 v[122:123], v[116:117], v[122:123]
	v_cvt_pk_bf16_f32 v120, v120, v121
	v_cvt_pk_bf16_f32 v121, v122, v123
	s_waitcnt lgkmcnt(3)
	v_mov_b32_e32 v122, v132
	s_waitcnt lgkmcnt(2)
	v_mov_b32_e32 v123, v134
	s_waitcnt lgkmcnt(1)
	v_mov_b32_e32 v140, v136
	s_waitcnt lgkmcnt(0)
	v_mov_b32_e32 v141, v138
	v_pk_mul_f32 v[122:123], v[118:119], v[122:123]
	v_pk_mul_f32 v[140:141], v[112:113], v[140:141]
	v_cvt_pk_bf16_f32 v122, v122, v123
	v_cvt_pk_bf16_f32 v123, v140, v141
	v_mad_i64_i32 v[140:141], s[0:1], s76, v102, 0
	v_lshl_add_u64 v[140:141], v[140:141], 1, s[18:19]
	v_lshl_add_u64 v[140:141], v[140:141], 0, v[38:39]
	v_mov_b32_e32 v126, v125
	v_mov_b32_e32 v130, v129
	global_store_dwordx4 v[140:141], v[120:123], off sc1
	v_mov_b32_e32 v134, v133
	v_mov_b32_e32 v138, v137
	v_pk_mul_f32 v[120:121], v[114:115], v[126:127]
	v_pk_mul_f32 v[122:123], v[116:117], v[130:131]
	v_cvt_pk_bf16_f32 v120, v120, v121
	v_cvt_pk_bf16_f32 v121, v122, v123
	v_pk_mul_f32 v[122:123], v[118:119], v[134:135]
	v_pk_mul_f32 v[124:125], v[112:113], v[138:139]
	v_cvt_pk_bf16_f32 v122, v122, v123
	v_cvt_pk_bf16_f32 v123, v124, v125
	v_mad_i64_i32 v[124:125], s[0:1], s76, v106, 0
	v_lshl_add_u64 v[124:125], v[124:125], 1, s[18:19]
	v_lshl_add_u64 v[124:125], v[124:125], 0, v[38:39]
	ds_read2_b32 v[126:127], v37 offset0:16 offset1:24
	ds_read2_b32 v[128:129], v37 offset0:49 offset1:57
	global_store_dwordx4 v[124:125], v[120:123], off sc1
	ds_read2_b32 v[124:125], v37 offset0:82 offset1:90
	ds_read2_b32 v[130:131], v37 offset0:115 offset1:123
	ds_read2_b32 v[132:133], v37 offset0:148 offset1:156
	ds_read2_b32 v[134:135], v37 offset0:181 offset1:189
	ds_read2_b32 v[136:137], v37 offset0:214 offset1:222
	ds_read2_b32 v[138:139], v37 offset0:247 offset1:255
	s_waitcnt lgkmcnt(7)
	v_mov_b32_e32 v120, v126
	s_waitcnt lgkmcnt(6)
	v_mov_b32_e32 v121, v128
	s_waitcnt lgkmcnt(5)
	v_mov_b32_e32 v122, v124
	s_waitcnt lgkmcnt(4)
	v_mov_b32_e32 v123, v130
	v_pk_mul_f32 v[120:121], v[114:115], v[120:121]
	v_pk_mul_f32 v[122:123], v[116:117], v[122:123]
	v_mov_b32_e32 v128, v127
	v_mov_b32_e32 v130, v125
	v_cvt_pk_bf16_f32 v120, v120, v121
	v_cvt_pk_bf16_f32 v121, v122, v123
	s_waitcnt lgkmcnt(3)
	v_mov_b32_e32 v122, v132
	s_waitcnt lgkmcnt(2)
	v_mov_b32_e32 v123, v134
	s_waitcnt lgkmcnt(1)
	v_mov_b32_e32 v140, v136
	s_waitcnt lgkmcnt(0)
	v_mov_b32_e32 v141, v138
	v_pk_mul_f32 v[114:115], v[114:115], v[128:129]
	v_pk_mul_f32 v[116:117], v[116:117], v[130:131]
	v_mov_b32_e32 v134, v133
	v_mov_b32_e32 v138, v137
	v_pk_mul_f32 v[122:123], v[118:119], v[122:123]
	v_pk_mul_f32 v[140:141], v[112:113], v[140:141]
	v_cvt_pk_bf16_f32 v114, v114, v115
	v_cvt_pk_bf16_f32 v115, v116, v117
	v_pk_mul_f32 v[116:117], v[118:119], v[134:135]
	v_pk_mul_f32 v[112:113], v[112:113], v[138:139]
	v_cvt_pk_bf16_f32 v122, v122, v123
	v_cvt_pk_bf16_f32 v123, v140, v141
	v_mad_i64_i32 v[140:141], s[0:1], s76, v108, 0
	v_cvt_pk_bf16_f32 v116, v116, v117
	v_cvt_pk_bf16_f32 v117, v112, v113
	v_mad_i64_i32 v[112:113], s[0:1], s76, v110, 0
	v_lshl_add_u64 v[140:141], v[140:141], 1, s[18:19]
	v_lshl_add_u64 v[112:113], v[112:113], 1, s[18:19]
	v_lshl_add_u64 v[140:141], v[140:141], 0, v[38:39]
	v_lshl_add_u64 v[112:113], v[112:113], 0, v[38:39]
	global_store_dwordx4 v[140:141], v[120:123], off sc1
	global_store_dwordx4 v[112:113], v[114:117], off sc1
	s_and_b64 vcc, exec, s[22:23]
	s_cbranch_vccz .LBB0_66
	s_branch .LBB0_242

.LBB0_257:
	s_or_b64 exec, exec, s[18:19]
	v_readlane_b32 s24, v253, 50
	v_readlane_b32 s25, v253, 51
	s_waitcnt vmcnt(0)
	v_cvt_pk_bf16_f32 v30, v30, v31
	v_cvt_pk_bf16_f32 v31, v32, v33
	v_cvt_pk_bf16_f32 v32, v26, v27
	v_cvt_pk_bf16_f32 v33, v28, v29
	v_lshl_add_u64 v[26:27], v[34:35], 4, s[24:25]
	global_store_dwordx4 v[26:27], v[30:33], off sc1
	s_and_saveexec_b64 s[6:7], vcc
	s_cbranch_execz .LBB0_260
	v_cvt_pk_bf16_f32 v26, v10, v11
	v_cvt_pk_bf16_f32 v27, v12, v13
	v_cvt_pk_bf16_f32 v28, v22, v23
	v_cvt_pk_bf16_f32 v29, v24, v25
	v_lshl_add_u64 v[30:31], v[36:37], 4, s[24:25]
	global_store_dwordx4 v[30:31], v[26:29], off sc1
	s_or_b64 exec, exec, s[6:7]
	s_and_saveexec_b64 s[6:7], s[0:1]
	s_cbranch_execnz .LBB0_261

.LBB0_261:
	v_cvt_pk_bf16_f32 v26, v6, v7
	v_cvt_pk_bf16_f32 v27, v8, v9
	v_cvt_pk_bf16_f32 v28, v18, v19
	v_cvt_pk_bf16_f32 v29, v20, v21
	v_lshl_add_u64 v[30:31], v[38:39], 4, s[24:25]
	global_store_dwordx4 v[30:31], v[26:29], off sc1
	s_or_b64 exec, exec, s[6:7]
	s_and_saveexec_b64 s[0:1], s[4:5]
	s_cbranch_execz .LBB0_250
.LBB0_262:
	v_cvt_pk_bf16_f32 v26, v2, v3
	v_cvt_pk_bf16_f32 v27, v4, v5
	v_cvt_pk_bf16_f32 v28, v14, v15
	v_cvt_pk_bf16_f32 v29, v16, v17
	v_lshl_add_u64 v[30:31], v[40:41], 4, s[24:25]
	global_store_dwordx4 v[30:31], v[26:29], off sc1
	s_branch .LBB0_250

.LBB0_823:
	s_or_b64 exec, exec, s[54:55]
	s_mul_hi_i32 s13, s60, 0x1800
	s_mulk_i32 s60, 0x1800
	s_add_u32 s12, s10, s60
	s_addc_u32 s13, s11, s13
	s_lshl_b32 s16, s6, 7
	s_add_u32 s54, s12, s16
	s_addc_u32 s55, s13, 0
	v_mov_b32_e32 v73, v0
	v_lshl_add_u64 v[6:7], s[54:55], 0, v[72:73]
	v_mov_b32_e32 v77, v0
	v_lshl_add_u64 v[10:11], v[6:7], 0, v[76:77]
	v_mov_b32_e32 v75, v0
	global_load_dwordx4 v[14:17], v[10:11], off offset:1024
	v_lshl_add_u64 v[6:7], s[54:55], 0, v[74:75]
	v_lshl_add_u64 v[8:9], v[6:7], 0, v[76:77]
	global_load_dwordx4 v[18:21], v[8:9], off offset:1024
	global_load_dwordx4 v[22:25], v[10:11], off offset:1056
	global_load_dwordx4 v[26:29], v[8:9], off offset:1056
	global_load_dwordx4 v[30:33], v[10:11], off offset:1088
	global_load_dwordx4 v[34:37], v[8:9], off offset:1088
	v_sub_f32_e32 v6, v12, v13
	v_mul_f32_e32 v6, 0x3fb8aa3b, v6
	v_exp_f32_e32 v6, v6
	v_cmp_gt_u32_e64 s[54:55], s7, v106
	v_add_u32_e32 v42, 0x2400, v108
	v_add_u32_e32 v43, 0x2c00, v108
	v_cndmask_b32_e64 v7, 0, v6, s[52:53]
	ds_bpermute_b32 v6, v103, v7
	ds_bpermute_b32 v13, v104, v7
	v_cmp_gt_u32_e64 s[52:53], s7, v105
	s_lshl_b32 s6, s6, 8
	s_add_u32 s6, s12, s6
	s_addc_u32 s7, s13, 0
	s_add_u32 s6, s6, s22
	s_addc_u32 s7, s7, 0
	v_add_u32_e32 v54, s2, v107
	v_mov_b32_e32 v79, v0
	v_mov_b32_e32 v81, v0
	v_mov_b32_e32 v83, v0
	s_waitcnt vmcnt(5)
	v_cndmask_b32_e64 v40, 0, v15, s[52:53]
	v_cndmask_b32_e64 v14, 0, v14, s[52:53]
	s_waitcnt vmcnt(4)
	v_cndmask_b32_e64 v15, 0, v18, s[54:55]
	v_cndmask_b32_e64 v41, 0, v21, s[54:55]
	v_cndmask_b32_e64 v19, 0, v19, s[54:55]
	v_lshlrev_b32_e32 v12, 16, v14
	v_lshlrev_b32_e32 v7, 16, v15
	v_cndmask_b32_e64 v38, 0, v17, s[52:53]
	v_cndmask_b32_e64 v39, 0, v16, s[52:53]
	v_cndmask_b32_e64 v44, 0, v20, s[54:55]
	s_waitcnt vmcnt(3)
	v_cndmask_b32_e64 v45, 0, v25, s[52:53]
	v_cndmask_b32_e64 v48, 0, v22, s[52:53]
	s_waitcnt vmcnt(2)
	v_cndmask_b32_e64 v51, 0, v27, s[54:55]
	v_cndmask_b32_e64 v52, 0, v26, s[54:55]
	v_and_b32_e32 v15, 0xffff0000, v15
	v_and_b32_e32 v14, 0xffff0000, v14
	v_lshlrev_b32_e32 v17, 16, v19
	v_lshlrev_b32_e32 v16, 16, v40
	v_and_b32_e32 v18, 0xffff0000, v40
	v_lshlrev_b32_e32 v25, 16, v41
	v_and_b32_e32 v27, 0xffff0000, v41
	s_waitcnt lgkmcnt(0)
	v_pk_mul_f32 v[40:41], v[12:13], v[6:7]
	v_mov_b32_e32 v7, v13
	v_cndmask_b32_e64 v46, 0, v24, s[52:53]
	v_cndmask_b32_e64 v47, 0, v23, s[52:53]
	v_cndmask_b32_e64 v49, 0, v29, s[54:55]
	v_cndmask_b32_e64 v50, 0, v28, s[54:55]
	v_and_b32_e32 v19, 0xffff0000, v19
	v_lshlrev_b32_e32 v21, 16, v44
	v_lshlrev_b32_e32 v20, 16, v39
	v_and_b32_e32 v23, 0xffff0000, v44
	v_and_b32_e32 v22, 0xffff0000, v39
	v_lshlrev_b32_e32 v24, 16, v38
	v_and_b32_e32 v26, 0xffff0000, v38
	v_lshlrev_b32_e32 v29, 16, v52
	v_lshlrev_b32_e32 v28, 16, v48
	v_and_b32_e32 v39, 0xffff0000, v52
	v_and_b32_e32 v38, 0xffff0000, v48
	v_pk_mul_f32 v[12:13], v[6:7], v[14:15]
	v_pk_mul_f32 v[14:15], v[6:7], v[16:17]
	v_cvt_pk_bf16_f32 v40, v40, v41
	v_pk_mul_f32 v[16:17], v[6:7], v[18:19]
	v_pk_mul_f32 v[18:19], v[6:7], v[20:21]
	v_pk_mul_f32 v[20:21], v[6:7], v[22:23]
	v_pk_mul_f32 v[22:23], v[6:7], v[24:25]
	v_pk_mul_f32 v[24:25], v[6:7], v[26:27]
	v_pk_mul_f32 v[26:27], v[6:7], v[28:29]
	v_pk_mul_f32 v[28:29], v[6:7], v[38:39]
	v_cvt_pk_bf16_f32 v12, v12, v13
	v_cvt_pk_bf16_f32 v13, v14, v15
	v_cvt_pk_bf16_f32 v14, v16, v17
	v_cvt_pk_bf16_f32 v15, v18, v19
	v_cvt_pk_bf16_f32 v16, v20, v21
	v_cvt_pk_bf16_f32 v17, v22, v23
	v_cvt_pk_bf16_f32 v18, v24, v25
	v_cvt_pk_bf16_f32 v19, v26, v27
	v_cvt_pk_bf16_f32 v20, v28, v29
	ds_write2_b32 v42, v40, v12 offset1:36
	ds_write2_b32 v42, v13, v14 offset0:72 offset1:108
	ds_write2_b32 v42, v15, v16 offset0:144 offset1:180
	ds_write_b32 v108, v17 offset:10080
	ds_write_b32 v109, v18 offset:9216
	ds_write2_b32 v43, v19, v20 offset0:64 offset1:100
	v_lshlrev_b32_e32 v13, 16, v51
	v_lshlrev_b32_e32 v12, 16, v47
	v_pk_mul_f32 v[12:13], v[6:7], v[12:13]
	s_waitcnt vmcnt(1)
	v_cndmask_b32_e64 v28, 0, v31, s[52:53]
	v_cvt_pk_bf16_f32 v14, v12, v13
	v_and_b32_e32 v13, 0xffff0000, v51
	v_and_b32_e32 v12, 0xffff0000, v47
	v_pk_mul_f32 v[12:13], v[6:7], v[12:13]
	s_waitcnt vmcnt(0)
	v_cndmask_b32_e64 v22, 0, v35, s[54:55]
	v_cvt_pk_bf16_f32 v15, v12, v13
	ds_write2_b32 v43, v14, v15 offset0:136 offset1:172
	v_lshlrev_b32_e32 v15, 16, v50
	v_lshlrev_b32_e32 v14, 16, v46
	global_load_dwordx4 v[10:13], v[10:11], off offset:1120
	v_pk_mul_f32 v[18:19], v[6:7], v[14:15]
	global_load_dwordx4 v[14:17], v[8:9], off offset:1120
	v_and_b32_e32 v9, 0xffff0000, v50
	v_and_b32_e32 v8, 0xffff0000, v46
	v_pk_mul_f32 v[8:9], v[6:7], v[8:9]
	v_cvt_pk_bf16_f32 v18, v18, v19
	v_cvt_pk_bf16_f32 v8, v8, v9
	ds_write2_b32 v43, v18, v8 offset0:208 offset1:244
	v_lshlrev_b32_e32 v9, 16, v49
	v_lshlrev_b32_e32 v8, 16, v45
	v_pk_mul_f32 v[8:9], v[6:7], v[8:9]
	v_cndmask_b32_e64 v18, 0, v30, s[52:53]
	v_cvt_pk_bf16_f32 v8, v8, v9
	ds_write_b32 v108, v8 offset:12384
	v_and_b32_e32 v9, 0xffff0000, v49
	v_and_b32_e32 v8, 0xffff0000, v45
	v_pk_mul_f32 v[8:9], v[6:7], v[8:9]
	v_cndmask_b32_e64 v19, 0, v34, s[54:55]
	v_cvt_pk_bf16_f32 v8, v8, v9
	ds_write_b32 v110, v8 offset:9216
	v_lshlrev_b32_e32 v9, 16, v19
	v_lshlrev_b32_e32 v8, 16, v18
	v_pk_mul_f32 v[8:9], v[6:7], v[8:9]
	v_add_u32_e32 v31, 0x3400, v108
	v_cvt_pk_bf16_f32 v20, v8, v9
	v_and_b32_e32 v9, 0xffff0000, v19
	v_and_b32_e32 v8, 0xffff0000, v18
	v_pk_mul_f32 v[8:9], v[6:7], v[8:9]
	v_cndmask_b32_e64 v27, 0, v32, s[52:53]
	v_cvt_pk_bf16_f32 v8, v8, v9
	ds_write2_b32 v31, v20, v8 offset0:128 offset1:164
	v_lshlrev_b32_e32 v9, 16, v22
	v_lshlrev_b32_e32 v8, 16, v28
	v_pk_mul_f32 v[8:9], v[6:7], v[8:9]
	v_cndmask_b32_e64 v29, 0, v37, s[54:55]
	v_cvt_pk_bf16_f32 v32, v8, v9
	v_lshl_add_u64 v[8:9], s[6:7], 0, v[72:73]
	v_lshl_add_u64 v[34:35], v[8:9], 0, v[76:77]
	v_and_b32_e32 v9, 0xffff0000, v22
	v_lshl_add_u64 v[22:23], s[6:7], 0, v[74:75]
	v_cndmask_b32_e64 v30, 0, v36, s[54:55]
	global_load_dwordx4 v[18:21], v[34:35], off offset:2048
	v_lshl_add_u64 v[36:37], v[22:23], 0, v[76:77]
	global_load_dwordx4 v[22:25], v[36:37], off offset:2048
	v_and_b32_e32 v8, 0xffff0000, v28
	v_pk_mul_f32 v[8:9], v[6:7], v[8:9]
	v_cndmask_b32_e64 v26, 0, v33, s[52:53]
	v_cvt_pk_bf16_f32 v8, v8, v9
	ds_write2_b32 v31, v32, v8 offset0:200 offset1:236
	v_lshlrev_b32_e32 v9, 16, v30
	v_lshlrev_b32_e32 v8, 16, v27
	v_pk_mul_f32 v[8:9], v[6:7], v[8:9]
	v_add_u32_e32 v41, 0x4000, v108
	v_cvt_pk_bf16_f32 v28, v8, v9
	v_and_b32_e32 v9, 0xffff0000, v30
	v_and_b32_e32 v8, 0xffff0000, v27
	v_pk_mul_f32 v[8:9], v[6:7], v[8:9]
	s_mul_i32 s6, s58, 0x4400
	v_cvt_pk_bf16_f32 v8, v8, v9
	v_add_u32_e32 v9, 0x3800, v108
	ds_write2_b32 v9, v28, v8 offset0:16 offset1:52
	v_lshlrev_b32_e32 v9, 16, v29
	v_lshlrev_b32_e32 v8, 16, v26
	v_pk_mul_f32 v[8:9], v[6:7], v[8:9]
	s_mul_hi_i32 s7, s58, 0x4400
	v_cvt_pk_bf16_f32 v8, v8, v9
	ds_write_b32 v108, v8 offset:14688
	v_and_b32_e32 v9, 0xffff0000, v29
	v_and_b32_e32 v8, 0xffff0000, v26
	v_pk_mul_f32 v[8:9], v[6:7], v[8:9]
	global_load_dwordx4 v[26:29], v[34:35], off offset:2080
	v_cvt_pk_bf16_f32 v8, v8, v9
	ds_write_b32 v111, v8 offset:9216
	s_add_u32 s6, s24, s6
	s_addc_u32 s7, s25, s7
	s_waitcnt vmcnt(4)
	v_cndmask_b32_e64 v31, 0, v10, s[52:53]
	v_cndmask_b32_e64 v38, 0, v13, s[52:53]
	s_waitcnt vmcnt(3)
	v_cndmask_b32_e64 v14, 0, v14, s[54:55]
	v_cndmask_b32_e64 v39, 0, v12, s[52:53]
	v_lshlrev_b32_e32 v13, 16, v14
	v_lshlrev_b32_e32 v12, 16, v31
	v_pk_mul_f32 v[12:13], v[6:7], v[12:13]
	v_cndmask_b32_e64 v32, 0, v16, s[54:55]
	v_cvt_pk_bf16_f32 v16, v12, v13
	v_and_b32_e32 v13, 0xffff0000, v14
	v_and_b32_e32 v12, 0xffff0000, v31
	v_cndmask_b32_e64 v30, 0, v11, s[52:53]
	global_load_dwordx4 v[8:11], v[36:37], off offset:2080
	v_pk_mul_f32 v[12:13], v[6:7], v[12:13]
	v_cndmask_b32_e64 v15, 0, v15, s[54:55]
	v_cvt_pk_bf16_f32 v12, v12, v13
	v_add_u32_e32 v13, 0x3c00, v108
	v_cndmask_b32_e64 v40, 0, v17, s[54:55]
	ds_write2_b32 v13, v16, v12 offset0:192 offset1:228
	v_lshlrev_b32_e32 v13, 16, v15
	v_lshlrev_b32_e32 v12, 16, v30
	v_lshlrev_b32_e32 v17, 16, v32
	v_lshlrev_b32_e32 v16, 16, v39
	v_pk_mul_f32 v[12:13], v[6:7], v[12:13]
	v_pk_mul_f32 v[16:17], v[6:7], v[16:17]
	v_cvt_pk_bf16_f32 v14, v12, v13
	v_and_b32_e32 v13, 0xffff0000, v15
	v_and_b32_e32 v12, 0xffff0000, v30
	v_cvt_pk_bf16_f32 v42, v16, v17
	v_and_b32_e32 v17, 0xffff0000, v32
	v_and_b32_e32 v16, 0xffff0000, v39
	v_pk_mul_f32 v[12:13], v[6:7], v[12:13]
	v_pk_mul_f32 v[16:17], v[6:7], v[16:17]
	v_cvt_pk_bf16_f32 v12, v12, v13
	v_cvt_pk_bf16_f32 v16, v16, v17
	ds_write2_b32 v41, v14, v12 offset0:8 offset1:44
	global_load_dwordx4 v[12:15], v[34:35], off offset:2112
	ds_write2_b32 v41, v42, v16 offset0:80 offset1:116
	v_lshlrev_b32_e32 v17, 16, v40
	v_lshlrev_b32_e32 v16, 16, v38
	global_load_dwordx4 v[30:33], v[36:37], off offset:2112
	v_pk_mul_f32 v[16:17], v[6:7], v[16:17]
	s_waitcnt vmcnt(4)
	v_cndmask_b32_e64 v39, 0, v23, s[54:55]
	v_cvt_pk_bf16_f32 v16, v16, v17
	ds_write_b32 v108, v16 offset:16992
	v_and_b32_e32 v17, 0xffff0000, v40
	v_and_b32_e32 v16, 0xffff0000, v38
	v_pk_mul_f32 v[6:7], v[6:7], v[16:17]
	v_cndmask_b32_e64 v16, 0, v18, s[52:53]
	v_cvt_pk_bf16_f32 v6, v6, v7
	v_cndmask_b32_e64 v17, 0, v22, s[54:55]
	v_and_b32_e32 v18, 0xffff, v16
	v_lshrrev_b32_e32 v16, 16, v16
	ds_write_b32 v112, v6 offset:9216
	v_cndmask_b32_e64 v6, 0, v21, s[52:53]
	v_cndmask_b32_e64 v7, 0, v20, s[52:53]
	v_cndmask_b32_e64 v38, 0, v19, s[52:53]
	v_lshl_or_b32 v20, v17, 16, v18
	v_and_or_b32 v21, v17, s3, v16
	global_load_dwordx4 v[16:19], v[34:35], off offset:2144
	ds_write2_b32 v108, v20, v21 offset1:36
	v_and_b32_e32 v20, 0xffff, v38
	v_lshl_or_b32 v34, v39, 16, v20
	global_load_dwordx4 v[20:23], v[36:37], off offset:2144
	v_lshrrev_b32_e32 v35, 16, v38
	v_and_or_b32 v35, v39, s3, v35
	v_cndmask_b32_e64 v24, 0, v24, s[54:55]
	ds_write2_b32 v108, v34, v35 offset0:72 offset1:108
	v_and_b32_e32 v34, 0xffff, v7
	v_lshrrev_b32_e32 v7, 16, v7
	v_lshl_or_b32 v34, v24, 16, v34
	v_and_or_b32 v7, v24, s3, v7
	v_cndmask_b32_e64 v25, 0, v25, s[54:55]
	ds_write2_b32 v108, v34, v7 offset0:144 offset1:180
	v_and_b32_e32 v7, 0xffff, v6
	v_lshrrev_b32_e32 v6, 16, v6
	v_lshl_or_b32 v7, v25, 16, v7
	v_and_or_b32 v6, v25, s3, v6
	s_waitcnt vmcnt(5)
	v_cndmask_b32_e64 v25, 0, v26, s[52:53]
	v_and_b32_e32 v26, 0xffff, v25
	v_lshrrev_b32_e32 v25, 16, v25
	v_cndmask_b32_e64 v24, 0, v27, s[52:53]
	ds_write_b32 v108, v7 offset:864
	ds_write_b32 v109, v6
	v_cndmask_b32_e64 v7, 0, v28, s[52:53]
	v_cndmask_b32_e64 v6, 0, v29, s[52:53]
	s_waitcnt vmcnt(4)
	v_cndmask_b32_e64 v8, 0, v8, s[54:55]
	v_lshl_or_b32 v26, v8, 16, v26
	v_and_or_b32 v8, v8, s3, v25
	v_add_u32_e32 v25, 0x800, v108
	v_cndmask_b32_e64 v9, 0, v9, s[54:55]
	ds_write2_b32 v25, v26, v8 offset0:64 offset1:100
	v_and_b32_e32 v8, 0xffff, v24
	v_lshrrev_b32_e32 v24, 16, v24
	v_lshl_or_b32 v8, v9, 16, v8
	v_and_or_b32 v9, v9, s3, v24
	v_cndmask_b32_e64 v10, 0, v10, s[54:55]
	ds_write2_b32 v25, v8, v9 offset0:136 offset1:172
	v_and_b32_e32 v8, 0xffff, v7
	v_lshrrev_b32_e32 v7, 16, v7
	v_lshl_or_b32 v8, v10, 16, v8
	v_and_or_b32 v7, v10, s3, v7
	v_cndmask_b32_e64 v11, 0, v11, s[54:55]
	ds_write2_b32 v25, v8, v7 offset0:208 offset1:244
	v_and_b32_e32 v7, 0xffff, v6
	v_lshl_or_b32 v7, v11, 16, v7
	ds_write_b32 v108, v7 offset:3168
	v_lshrrev_b32_e32 v6, 16, v6
	v_and_or_b32 v6, v11, s3, v6
	ds_write_b32 v110, v6
	s_waitcnt vmcnt(3)
	v_cndmask_b32_e64 v9, 0, v12, s[52:53]
	v_cndmask_b32_e64 v7, 0, v14, s[52:53]
	v_cndmask_b32_e64 v8, 0, v13, s[52:53]
	v_and_b32_e32 v14, 0xffff, v9
	s_waitcnt vmcnt(2)
	v_cndmask_b32_e64 v13, 0, v30, s[54:55]
	v_lshrrev_b32_e32 v9, 16, v9
	v_lshl_or_b32 v14, v13, 16, v14
	v_and_or_b32 v9, v13, s3, v9
	v_add_u32_e32 v13, 0x1000, v108
	v_cndmask_b32_e64 v12, 0, v31, s[54:55]
	ds_write2_b32 v13, v14, v9 offset0:128 offset1:164
	v_and_b32_e32 v9, 0xffff, v8
	v_lshrrev_b32_e32 v8, 16, v8
	v_lshl_or_b32 v9, v12, 16, v9
	v_and_or_b32 v8, v12, s3, v8
	v_cndmask_b32_e64 v11, 0, v32, s[54:55]
	ds_write2_b32 v13, v9, v8 offset0:200 offset1:236
	v_and_b32_e32 v8, 0xffff, v7
	v_lshrrev_b32_e32 v7, 16, v7
	v_lshl_or_b32 v8, v11, 16, v8
	v_and_or_b32 v7, v11, s3, v7
	v_add_u32_e32 v9, 0x1400, v108
	v_cndmask_b32_e64 v6, 0, v15, s[52:53]
	ds_write2_b32 v9, v8, v7 offset0:16 offset1:52
	v_cndmask_b32_e64 v10, 0, v33, s[54:55]
	s_waitcnt vmcnt(1)
	v_cndmask_b32_e64 v9, 0, v16, s[52:53]
	v_and_b32_e32 v7, 0xffff, v6
	v_lshrrev_b32_e32 v6, 16, v6
	v_and_b32_e32 v14, 0xffff, v9
	s_waitcnt vmcnt(0)
	v_cndmask_b32_e64 v13, 0, v20, s[54:55]
	v_lshrrev_b32_e32 v9, 16, v9
	v_lshl_or_b32 v7, v10, 16, v7
	v_and_or_b32 v6, v10, s3, v6
	v_cndmask_b32_e64 v8, 0, v17, s[52:53]
	v_lshl_or_b32 v14, v13, 16, v14
	v_and_or_b32 v9, v13, s3, v9
	v_add_u32_e32 v13, 0x1800, v108
	ds_write_b32 v108, v7 offset:5472
	ds_write_b32 v111, v6
	v_cndmask_b32_e64 v12, 0, v21, s[54:55]
	ds_write2_b32 v13, v14, v9 offset0:192 offset1:228
	v_and_b32_e32 v9, 0xffff, v8
	v_lshrrev_b32_e32 v8, 16, v8
	v_cndmask_b32_e64 v7, 0, v18, s[52:53]
	v_lshl_or_b32 v9, v12, 16, v9
	v_and_or_b32 v8, v12, s3, v8
	v_add_u32_e32 v12, 0x1c00, v108
	v_cndmask_b32_e64 v11, 0, v22, s[54:55]
	ds_write2_b32 v12, v9, v8 offset0:8 offset1:44
	v_and_b32_e32 v8, 0xffff, v7
	v_lshrrev_b32_e32 v7, 16, v7
	v_cndmask_b32_e64 v6, 0, v19, s[52:53]
	v_lshl_or_b32 v8, v11, 16, v8
	v_and_or_b32 v7, v11, s3, v7
	v_cndmask_b32_e64 v10, 0, v23, s[54:55]
	ds_write2_b32 v12, v8, v7 offset0:80 offset1:116
	v_and_b32_e32 v7, 0xffff, v6
	v_lshrrev_b32_e32 v6, 16, v6
	v_lshl_or_b32 v7, v10, 16, v7
	v_and_or_b32 v6, v10, s3, v6
	ds_write_b32 v108, v7 offset:7776
	ds_write_b32 v112, v6
	ds_read_b128 v[6:9], v54 offset:9216
	ds_read_b128 v[10:13], v54
	ds_read_b128 v[14:17], v54 offset:9280
	ds_read_b128 v[18:21], v54 offset:64
	ds_read_b128 v[26:29], v54 offset:2304
	ds_read_b128 v[30:33], v54 offset:4608
	ds_read_b128 v[42:45], v113
	ds_read_b128 v[84:87], v113 offset:64
	ds_read_b128 v[50:53], v54 offset:11520
	ds_read_b128 v[54:57], v54 offset:13824
	s_waitcnt lgkmcnt(1)
	v_mfma_f32_16x16x32_bf16 v[58:61], v[50:53], v[10:13], 0
	v_mfma_f32_16x16x32_bf16 v[88:91], v[50:53], v[26:29], 0
	v_mfma_f32_16x16x32_bf16 v[116:119], v[50:53], v[30:33], 0
	v_mfma_f32_16x16x32_bf16 v[120:123], v[50:53], v[42:45], 0
	v_mfma_f32_16x16x32_bf16 v[124:127], v[50:53], v[2:5], 0
	ds_read_b128 v[50:53], v113 offset:9216
	ds_read_b128 v[148:151], v113 offset:9280
	ds_read_b128 v[176:179], v114 offset:2304
	ds_read_b128 v[180:183], v114 offset:4608
	v_mfma_f32_16x16x32_bf16 v[22:25], v[6:9], v[10:13], 0
	v_mfma_f32_16x16x32_bf16 v[34:37], v[6:9], v[26:29], 0
	v_mfma_f32_16x16x32_bf16 v[38:41], v[6:9], v[30:33], 0
	v_mfma_f32_16x16x32_bf16 v[46:49], v[6:9], v[42:45], 0
	v_mfma_f32_16x16x32_bf16 v[6:9], v[6:9], v[2:5], 0
	v_mfma_f32_16x16x32_bf16 v[172:175], v[14:17], v[18:21], v[22:25]
	s_waitcnt lgkmcnt(1)
	v_mfma_f32_16x16x32_bf16 v[184:187], v[14:17], v[176:179], v[34:37]
	s_waitcnt lgkmcnt(0)
	v_mfma_f32_16x16x32_bf16 v[188:191], v[14:17], v[180:183], v[38:41]
	v_mfma_f32_16x16x32_bf16 v[192:195], v[14:17], v[84:87], v[46:49]
	v_mfma_f32_16x16x32_bf16 v[66:69], v[14:17], v[2:5], v[6:9]
	s_nop 2
	ds_read_b128 v[6:9], v114 offset:11520
	ds_read_b128 v[14:17], v114 offset:13824
	v_mfma_f32_16x16x32_bf16 v[128:131], v[54:57], v[10:13], 0
	v_mfma_f32_16x16x32_bf16 v[140:143], v[54:57], v[42:45], 0
	v_mfma_f32_16x16x32_bf16 v[10:13], v[50:53], v[10:13], 0
	v_mfma_f32_16x16x32_bf16 v[164:167], v[50:53], v[42:45], 0
	v_mfma_f32_16x16x32_bf16 v[132:135], v[54:57], v[26:29], 0
	v_mfma_f32_16x16x32_bf16 v[136:139], v[54:57], v[30:33], 0
	v_mfma_f32_16x16x32_bf16 v[144:147], v[54:57], v[2:5], 0
	v_mfma_f32_16x16x32_bf16 v[152:155], v[50:53], v[26:29], 0
	v_mfma_f32_16x16x32_bf16 v[156:159], v[50:53], v[30:33], 0
	v_mfma_f32_16x16x32_bf16 v[168:171], v[50:53], v[2:5], 0
	s_waitcnt lgkmcnt(1)
	v_mfma_f32_16x16x32_bf16 v[62:65], v[6:9], v[18:21], v[58:61]
	v_mfma_f32_16x16x32_bf16 v[58:61], v[6:9], v[176:179], v[88:91]
	v_mfma_f32_16x16x32_bf16 v[50:53], v[6:9], v[84:87], v[120:123]
	s_waitcnt lgkmcnt(0)
	v_mfma_f32_16x16x32_bf16 v[30:33], v[14:17], v[84:87], v[140:143]
	v_mfma_f32_16x16x32_bf16 v[22:25], v[148:151], v[18:21], v[10:13]
	v_mfma_f32_16x16x32_bf16 v[10:13], v[148:151], v[84:87], v[164:167]
	v_mfma_f32_16x16x32_bf16 v[54:57], v[6:9], v[180:183], v[116:119]
	v_mfma_f32_16x16x32_bf16 v[46:49], v[6:9], v[2:5], v[124:127]
	v_mfma_f32_16x16x32_bf16 v[42:45], v[14:17], v[18:21], v[128:131]
	v_mfma_f32_16x16x32_bf16 v[38:41], v[14:17], v[176:179], v[132:135]
	v_mfma_f32_16x16x32_bf16 v[34:37], v[14:17], v[180:183], v[136:139]
	v_mfma_f32_16x16x32_bf16 v[26:29], v[14:17], v[2:5], v[144:147]
	v_mfma_f32_16x16x32_bf16 v[18:21], v[148:151], v[176:179], v[152:155]
	v_mfma_f32_16x16x32_bf16 v[14:17], v[148:151], v[180:183], v[156:159]
	v_mfma_f32_16x16x32_bf16 v[6:9], v[148:151], v[2:5], v[168:171]
	v_and_b32_e32 v200, 15, v207
	v_lshrrev_b32_e32 v201, 4, v207
	v_mul_u32_u24_e32 v202, 0x90, v200
	v_lshl_add_u32 v202, v201, 3, v202
	v_add_u32_e32 v202, s2, v202
	v_lshrrev_b32_e32 v203, 3, v207
	v_and_b32_e32 v204, 7, v207
	v_mul_u32_u24_e32 v203, 0x90, v203
	v_lshl_add_u32 v203, v204, 4, v203
	v_add_u32_e32 v203, s2, v203
	s_lshl_b32 s16, s22, 6
	v_lshlrev_b32_e32 v198, 4, v207
	v_add_u32_e32 v198, s16, v198
	v_mov_b32_e32 v199, 0
	v_lshl_add_u64 v[196:197], s[6:7], 0, v[198:199]
	v_lshl_add_u64 v[88:89], s[6:7], 0, v[78:79]
	s_mov_b64 s[6:7], 0x4000
	v_lshl_add_u64 v[84:85], v[88:89], 0, s[6:7]
	s_mov_b64 s[6:7], 0x1000
	v_lshl_add_u64 v[204:205], v[196:197], 0, s[6:7]
	v_cvt_pk_bf16_f32 v172, v172, v173
	v_cvt_pk_bf16_f32 v173, v174, v175
	ds_write_b64 v202, v[172:173]
	v_cvt_pk_bf16_f32 v184, v184, v185
	v_cvt_pk_bf16_f32 v185, v186, v187
	ds_write_b64 v202, v[184:185] offset:2304
	v_cvt_pk_bf16_f32 v188, v188, v189
	v_cvt_pk_bf16_f32 v189, v190, v191
	ds_write_b64 v202, v[188:189] offset:4608
	v_cvt_pk_bf16_f32 v192, v192, v193
	v_cvt_pk_bf16_f32 v193, v194, v195
	ds_write_b64 v202, v[192:193] offset:6912
	v_cvt_pk_bf16_f32 v62, v62, v63
	v_cvt_pk_bf16_f32 v63, v64, v65
	ds_write_b64 v202, v[62:63] offset:32
	v_cvt_pk_bf16_f32 v58, v58, v59
	v_cvt_pk_bf16_f32 v59, v60, v61
	ds_write_b64 v202, v[58:59] offset:2336
	v_cvt_pk_bf16_f32 v54, v54, v55
	v_cvt_pk_bf16_f32 v55, v56, v57
	ds_write_b64 v202, v[54:55] offset:4640
	v_cvt_pk_bf16_f32 v50, v50, v51
	v_cvt_pk_bf16_f32 v51, v52, v53
	ds_write_b64 v202, v[50:51] offset:6944
	v_cvt_pk_bf16_f32 v42, v42, v43
	v_cvt_pk_bf16_f32 v43, v44, v45
	ds_write_b64 v202, v[42:43] offset:64
	v_cvt_pk_bf16_f32 v38, v38, v39
	v_cvt_pk_bf16_f32 v39, v40, v41
	ds_write_b64 v202, v[38:39] offset:2368
	v_cvt_pk_bf16_f32 v34, v34, v35
	v_cvt_pk_bf16_f32 v35, v36, v37
	ds_write_b64 v202, v[34:35] offset:4672
	v_cvt_pk_bf16_f32 v30, v30, v31
	v_cvt_pk_bf16_f32 v31, v32, v33
	ds_write_b64 v202, v[30:31] offset:6976
	v_cvt_pk_bf16_f32 v22, v22, v23
	v_cvt_pk_bf16_f32 v23, v24, v25
	ds_write_b64 v202, v[22:23] offset:96
	v_cvt_pk_bf16_f32 v18, v18, v19
	v_cvt_pk_bf16_f32 v19, v20, v21
	ds_write_b64 v202, v[18:19] offset:2400
	v_cvt_pk_bf16_f32 v14, v14, v15
	v_cvt_pk_bf16_f32 v15, v16, v17
	ds_write_b64 v202, v[14:15] offset:4704
	v_cvt_pk_bf16_f32 v10, v10, v11
	v_cvt_pk_bf16_f32 v11, v12, v13
	ds_write_b64 v202, v[10:11] offset:7008
	s_waitcnt lgkmcnt(0)
	ds_read_b128 v[208:211], v203
	ds_read_b128 v[212:215], v203 offset:1152
	ds_read_b128 v[216:219], v203 offset:2304
	ds_read_b128 v[220:223], v203 offset:3456
	ds_read_b128 v[224:227], v203 offset:4608
	ds_read_b128 v[228:231], v203 offset:5760
	ds_read_b128 v[172:175], v203 offset:6912
	ds_read_b128 v[184:187], v203 offset:8064
	s_waitcnt lgkmcnt(7)
	global_store_dwordx4 v[196:197], v[208:211], off sc1
	s_waitcnt lgkmcnt(6)
	global_store_dwordx4 v[196:197], v[212:215], off offset:1024 sc1
	s_waitcnt lgkmcnt(5)
	global_store_dwordx4 v[196:197], v[216:219], off offset:2048 sc1
	s_waitcnt lgkmcnt(4)
	global_store_dwordx4 v[196:197], v[220:223], off offset:3072 sc1
	s_waitcnt lgkmcnt(3)
	global_store_dwordx4 v[204:205], v[224:227], off sc1
	s_waitcnt lgkmcnt(2)
	global_store_dwordx4 v[204:205], v[228:231], off offset:1024 sc1
	s_waitcnt lgkmcnt(1)
	global_store_dwordx4 v[204:205], v[172:175], off offset:2048 sc1
	s_waitcnt lgkmcnt(0)
	global_store_dwordx4 v[204:205], v[184:187], off offset:3072 sc1
	s_and_saveexec_b64 s[52:53], s[50:51]
	s_cbranch_execz .LBB0_816
	v_cvt_pk_bf16_f32 v66, v66, v67
	v_cvt_pk_bf16_f32 v67, v68, v69
	global_store_dwordx2 v[84:85], v[66:67], off
	v_cvt_pk_bf16_f32 v46, v46, v47
	v_cvt_pk_bf16_f32 v47, v48, v49
	global_store_dwordx2 v[84:85], v[46:47], off offset:32
	v_cvt_pk_bf16_f32 v26, v26, v27
	v_cvt_pk_bf16_f32 v27, v28, v29
	global_store_dwordx2 v[84:85], v[26:27], off offset:64
	v_cvt_pk_bf16_f32 v6, v6, v7
	v_cvt_pk_bf16_f32 v7, v8, v9
	global_store_dwordx2 v[84:85], v[6:7], off offset:96
	s_branch .LBB0_816
